# asym P0 0/1/4/6 + nt on FF1 HID stores and FF2 final output stores
# baseline (speedup 1.0000x reference)
.LBB0_571:
	v_mov_b32_e32 v161, v164
	v_mov_b32_e32 v128, v165
	s_lshl_b32 s17, s72, 8
	s_or_b32 s17, s17, s66
	v_lshlrev_b32_e32 v160, 3, v128
	v_add_u32_e32 v128, s17, v160
	s_lshl_b32 s17, s26, 8
	s_and_b32 s28, s17, 0xfffff000
	s_ashr_i32 s29, s28, 31
	s_lshl_b64 s[28:29], s[28:29], 2
	s_add_u32 s28, s59, s28
	s_addc_u32 s29, s61, s29
	v_ashrrev_i32_e32 v129, 31, v128
	v_lshl_add_u64 v[128:129], v[128:129], 2, s[28:29]
	global_load_dwordx4 v[140:143], v[128:129], off
	global_load_dwordx4 v[136:139], v[128:129], off offset:16
	global_load_dwordx4 v[132:135], v[128:129], off offset:512
	s_nop 0
	global_load_dwordx4 v[128:131], v[128:129], off offset:528
	v_add_u32_e32 v162, s57, v161
	v_lshl_add_u32 v170, v162, 2, 0
	s_lshl_b32 s17, s72, 3
	v_add_u32_e32 v170, 0x22400, v170
	s_or_b32 s28, s17, s56
	s_ashr_i32 s27, s26, 31
	ds_read2_b32 v[172:173], v170 offset1:16
	s_ashr_i32 s29, s28, 31
	s_lshl_b64 s[26:27], s[26:27], 21
	s_lshl_b64 s[28:29], s[28:29], 14
	s_add_u32 s17, s64, s26
	s_addc_u32 s19, s65, s27
	v_ashrrev_i32_e32 v163, 31, v162
	s_add_u32 s26, s17, s28
	v_lshlrev_b64 v[162:163], 6, v[162:163]
	s_addc_u32 s27, s19, s29
	v_ashrrev_i32_e32 v161, 31, v160
	v_lshl_add_u64 v[162:163], s[26:27], 0, v[162:163]
	s_waitcnt lgkmcnt(0)
	v_mov_b32_e32 v174, v173
	v_lshl_add_u64 v[160:161], v[160:161], 1, v[162:163]
	v_add_co_u32_e32 v162, vcc, s49, v160
	s_waitcnt vmcnt(0)
	v_pk_fma_f32 v[126:127], v[126:127], v[172:173], v[142:143] op_sel_hi:[1,0,1]
	v_pk_fma_f32 v[124:125], v[124:125], v[172:173], v[140:141] op_sel_hi:[1,0,1]
	v_pk_fma_f32 v[122:123], v[122:123], v[172:173], v[138:139] op_sel_hi:[1,0,1]
	v_pk_fma_f32 v[120:121], v[120:121], v[172:173], v[136:137] op_sel_hi:[1,0,1]
	v_pk_fma_f32 v[110:111], v[110:111], v[172:173], v[134:135] op_sel_hi:[1,0,1]
	v_pk_fma_f32 v[108:109], v[108:109], v[172:173], v[132:133] op_sel_hi:[1,0,1]
	v_pk_fma_f32 v[106:107], v[106:107], v[172:173], v[130:131] op_sel_hi:[1,0,1]
	v_pk_fma_f32 v[104:105], v[104:105], v[172:173], v[128:129] op_sel_hi:[1,0,1]
	v_max_f32_e32 v124, 0, v124
	v_max_f32_e32 v120, 0, v120
	v_max_f32_e32 v125, 0, v125
	v_max_f32_e32 v121, 0, v121
	v_max_f32_e32 v126, 0, v126
	v_max_f32_e32 v122, 0, v122
	v_max_f32_e32 v127, 0, v127
	v_max_f32_e32 v123, 0, v123
	v_max_f32_e32 v108, 0, v108
	v_max_f32_e32 v104, 0, v104
	v_max_f32_e32 v109, 0, v109
	v_max_f32_e32 v105, 0, v105
	v_max_f32_e32 v110, 0, v110
	v_max_f32_e32 v106, 0, v106
	v_max_f32_e32 v111, 0, v111
	v_max_f32_e32 v107, 0, v107
	v_pk_mul_f32 v[124:125], v[124:125], v[124:125]
	v_pk_mul_f32 v[120:121], v[120:121], v[120:121]
	v_pk_mul_f32 v[126:127], v[126:127], v[126:127]
	v_pk_mul_f32 v[122:123], v[122:123], v[122:123]
	v_pk_mul_f32 v[108:109], v[108:109], v[108:109]
	v_pk_mul_f32 v[172:173], v[104:105], v[104:105]
	v_pk_mul_f32 v[110:111], v[110:111], v[110:111]
	v_pk_mul_f32 v[176:177], v[106:107], v[106:107]
	v_pk_fma_f32 v[118:119], v[118:119], v[174:175], v[142:143] op_sel_hi:[1,0,1]
	v_pk_fma_f32 v[116:117], v[116:117], v[174:175], v[140:141] op_sel_hi:[1,0,1]
	v_pk_fma_f32 v[114:115], v[114:115], v[174:175], v[138:139] op_sel_hi:[1,0,1]
	v_pk_fma_f32 v[112:113], v[112:113], v[174:175], v[136:137] op_sel_hi:[1,0,1]
	v_cvt_pk_bf16_f32 v104, v124, v125
	v_cvt_pk_bf16_f32 v105, v126, v127
	v_cvt_pk_bf16_f32 v106, v120, v121
	v_cvt_pk_bf16_f32 v107, v122, v123
	v_cvt_pk_bf16_f32 v108, v108, v109
	v_cvt_pk_bf16_f32 v109, v110, v111
	v_cvt_pk_bf16_f32 v110, v172, v173
	v_cvt_pk_bf16_f32 v111, v176, v177
	v_addc_co_u32_e32 v163, vcc, 0, v161, vcc
	v_max_f32_e32 v116, 0, v116
	v_max_f32_e32 v112, 0, v112
	v_max_f32_e32 v117, 0, v117
	global_store_dwordx4 v[160:161], v[104:107], off nt
	global_store_dwordx4 v[162:163], v[108:111], off nt
	v_max_f32_e32 v113, 0, v113
	v_pk_mul_f32 v[104:105], v[116:117], v[116:117]
	v_max_f32_e32 v108, 0, v118
	v_max_f32_e32 v110, 0, v114
	v_max_f32_e32 v109, 0, v119
	v_max_f32_e32 v111, 0, v115
	v_pk_mul_f32 v[106:107], v[112:113], v[112:113]
	v_pk_mul_f32 v[108:109], v[108:109], v[108:109]
	v_pk_mul_f32 v[110:111], v[110:111], v[110:111]
	v_pk_fma_f32 v[100:101], v[100:101], v[174:175], v[132:133] op_sel_hi:[1,0,1]
	v_pk_fma_f32 v[96:97], v[96:97], v[174:175], v[128:129] op_sel_hi:[1,0,1]
	v_cvt_pk_bf16_f32 v104, v104, v105
	v_cvt_pk_bf16_f32 v105, v108, v109
	v_cvt_pk_bf16_f32 v106, v106, v107
	v_cvt_pk_bf16_f32 v107, v110, v111
	v_pk_fma_f32 v[102:103], v[102:103], v[174:175], v[134:135] op_sel_hi:[1,0,1]
	v_max_f32_e32 v100, 0, v100
	v_max_f32_e32 v96, 0, v96
	v_max_f32_e32 v101, 0, v101
	v_max_f32_e32 v97, 0, v97
	global_store_dwordx4 v[160:161], v[104:107], off offset:1024 nt
	v_pk_mul_f32 v[100:101], v[100:101], v[100:101]
	v_pk_fma_f32 v[98:99], v[98:99], v[174:175], v[130:131] op_sel_hi:[1,0,1]
	v_pk_mul_f32 v[104:105], v[96:97], v[96:97]
	v_max_f32_e32 v96, 0, v102
	v_max_f32_e32 v97, 0, v103
	v_pk_mul_f32 v[102:103], v[96:97], v[96:97]
	v_cvt_pk_bf16_f32 v96, v100, v101
	ds_read2_b32 v[100:101], v170 offset0:32 offset1:48
	v_max_f32_e32 v98, 0, v98
	v_max_f32_e32 v99, 0, v99
	v_pk_mul_f32 v[106:107], v[98:99], v[98:99]
	v_cvt_pk_bf16_f32 v97, v102, v103
	s_waitcnt lgkmcnt(0)
	v_pk_fma_f32 v[88:89], v[88:89], v[100:101], v[136:137] op_sel_hi:[1,0,1]
	v_cvt_pk_bf16_f32 v98, v104, v105
	v_cvt_pk_bf16_f32 v99, v106, v107
	v_pk_fma_f32 v[94:95], v[94:95], v[100:101], v[142:143] op_sel_hi:[1,0,1]
	v_pk_fma_f32 v[92:93], v[92:93], v[100:101], v[140:141] op_sel_hi:[1,0,1]
	v_pk_fma_f32 v[90:91], v[90:91], v[100:101], v[138:139] op_sel_hi:[1,0,1]
	v_max_f32_e32 v88, 0, v88
	v_max_f32_e32 v89, 0, v89
	global_store_dwordx4 v[162:163], v[96:99], off offset:1024 nt
	v_max_f32_e32 v92, 0, v92
	v_max_f32_e32 v93, 0, v93
	v_pk_mul_f32 v[96:97], v[88:89], v[88:89]
	v_max_f32_e32 v88, 0, v94
	v_max_f32_e32 v90, 0, v90
	v_max_f32_e32 v89, 0, v95
	v_max_f32_e32 v91, 0, v91
	v_pk_mul_f32 v[92:93], v[92:93], v[92:93]
	v_pk_mul_f32 v[94:95], v[88:89], v[88:89]
	v_pk_mul_f32 v[98:99], v[90:91], v[90:91]
	v_pk_fma_f32 v[80:81], v[80:81], v[100:101], v[128:129] op_sel_hi:[1,0,1]
	v_cvt_pk_bf16_f32 v88, v92, v93
	v_cvt_pk_bf16_f32 v89, v94, v95
	v_cvt_pk_bf16_f32 v90, v96, v97
	v_cvt_pk_bf16_f32 v91, v98, v99
	v_pk_fma_f32 v[86:87], v[86:87], v[100:101], v[134:135] op_sel_hi:[1,0,1]
	v_pk_fma_f32 v[84:85], v[84:85], v[100:101], v[132:133] op_sel_hi:[1,0,1]
	v_pk_fma_f32 v[82:83], v[82:83], v[100:101], v[130:131] op_sel_hi:[1,0,1]
	v_max_f32_e32 v80, 0, v80
	v_max_f32_e32 v81, 0, v81
	global_store_dwordx4 v[160:161], v[88:91], off offset:2048 nt
	v_max_f32_e32 v84, 0, v84
	v_max_f32_e32 v85, 0, v85
	v_pk_mul_f32 v[88:89], v[80:81], v[80:81]
	v_max_f32_e32 v80, 0, v86
	v_max_f32_e32 v82, 0, v82
	v_max_f32_e32 v81, 0, v87
	v_max_f32_e32 v83, 0, v83
	v_pk_mul_f32 v[84:85], v[84:85], v[84:85]
	v_pk_mul_f32 v[86:87], v[80:81], v[80:81]
	v_pk_mul_f32 v[90:91], v[82:83], v[82:83]
	v_cvt_pk_bf16_f32 v80, v84, v85
	v_cvt_pk_bf16_f32 v81, v86, v87
	v_cvt_pk_bf16_f32 v82, v88, v89
	v_cvt_pk_bf16_f32 v83, v90, v91
	global_store_dwordx4 v[162:163], v[80:83], off offset:2048 nt
	s_nop 1
	v_mov_b32_e32 v80, v101
	v_pk_fma_f32 v[72:73], v[72:73], v[80:81], v[136:137] op_sel_hi:[1,0,1]
	v_pk_fma_f32 v[78:79], v[78:79], v[80:81], v[142:143] op_sel_hi:[1,0,1]
	v_pk_fma_f32 v[76:77], v[76:77], v[80:81], v[140:141] op_sel_hi:[1,0,1]
	v_pk_fma_f32 v[74:75], v[74:75], v[80:81], v[138:139] op_sel_hi:[1,0,1]
	v_max_f32_e32 v72, 0, v72
	v_max_f32_e32 v73, 0, v73
	v_max_f32_e32 v76, 0, v76
	v_max_f32_e32 v77, 0, v77
	v_pk_mul_f32 v[82:83], v[72:73], v[72:73]
	v_max_f32_e32 v72, 0, v78
	v_max_f32_e32 v74, 0, v74
	v_max_f32_e32 v73, 0, v79
	v_max_f32_e32 v75, 0, v75
	v_pk_mul_f32 v[76:77], v[76:77], v[76:77]
	v_pk_mul_f32 v[78:79], v[72:73], v[72:73]
	v_pk_mul_f32 v[84:85], v[74:75], v[74:75]
	v_pk_fma_f32 v[68:69], v[68:69], v[80:81], v[132:133] op_sel_hi:[1,0,1]
	v_pk_fma_f32 v[64:65], v[64:65], v[80:81], v[128:129] op_sel_hi:[1,0,1]
	v_cvt_pk_bf16_f32 v72, v76, v77
	v_cvt_pk_bf16_f32 v73, v78, v79
	v_cvt_pk_bf16_f32 v74, v82, v83
	v_cvt_pk_bf16_f32 v75, v84, v85
	v_pk_fma_f32 v[70:71], v[70:71], v[80:81], v[134:135] op_sel_hi:[1,0,1]
	v_max_f32_e32 v68, 0, v68
	v_max_f32_e32 v64, 0, v64
	v_max_f32_e32 v69, 0, v69
	v_max_f32_e32 v65, 0, v65
	global_store_dwordx4 v[160:161], v[72:75], off offset:3072 nt
	v_pk_mul_f32 v[68:69], v[68:69], v[68:69]
	v_pk_fma_f32 v[66:67], v[66:67], v[80:81], v[130:131] op_sel_hi:[1,0,1]
	v_pk_mul_f32 v[72:73], v[64:65], v[64:65]
	v_max_f32_e32 v64, 0, v70
	v_max_f32_e32 v65, 0, v71
	v_pk_mul_f32 v[70:71], v[64:65], v[64:65]
	v_cvt_pk_bf16_f32 v64, v68, v69
	ds_read2_b32 v[68:69], v170 offset0:128 offset1:144
	v_max_f32_e32 v66, 0, v66
	v_max_f32_e32 v67, 0, v67
	v_pk_mul_f32 v[74:75], v[66:67], v[66:67]
	v_cvt_pk_bf16_f32 v65, v70, v71
	s_waitcnt lgkmcnt(0)
	v_pk_fma_f32 v[60:61], v[60:61], v[68:69], v[140:141] op_sel_hi:[1,0,1]
	v_pk_fma_f32 v[56:57], v[56:57], v[68:69], v[136:137] op_sel_hi:[1,0,1]
	v_cvt_pk_bf16_f32 v66, v72, v73
	v_cvt_pk_bf16_f32 v67, v74, v75
	v_pk_fma_f32 v[62:63], v[62:63], v[68:69], v[142:143] op_sel_hi:[1,0,1]
	v_pk_fma_f32 v[58:59], v[58:59], v[68:69], v[138:139] op_sel_hi:[1,0,1]
	v_max_f32_e32 v60, 0, v60
	v_max_f32_e32 v56, 0, v56
	v_max_f32_e32 v61, 0, v61
	v_max_f32_e32 v57, 0, v57
	global_store_dwordx4 v[162:163], v[64:67], off offset:3072 nt
	v_pk_mul_f32 v[60:61], v[60:61], v[60:61]
	v_max_f32_e32 v58, 0, v58
	v_pk_mul_f32 v[64:65], v[56:57], v[56:57]
	v_max_f32_e32 v56, 0, v62
	v_max_f32_e32 v57, 0, v63
	v_max_f32_e32 v59, 0, v59
	v_pk_mul_f32 v[62:63], v[56:57], v[56:57]
	v_pk_mul_f32 v[66:67], v[58:59], v[58:59]
	v_cvt_pk_bf16_f32 v56, v60, v61
	v_add_co_u32_e32 v60, vcc, s51, v160
	v_pk_fma_f32 v[52:53], v[52:53], v[68:69], v[132:133] op_sel_hi:[1,0,1]
	v_pk_fma_f32 v[48:49], v[48:49], v[68:69], v[128:129] op_sel_hi:[1,0,1]
	v_cvt_pk_bf16_f32 v57, v62, v63
	v_cvt_pk_bf16_f32 v58, v64, v65
	v_cvt_pk_bf16_f32 v59, v66, v67
	v_addc_co_u32_e32 v61, vcc, 0, v161, vcc
	v_pk_fma_f32 v[54:55], v[54:55], v[68:69], v[134:135] op_sel_hi:[1,0,1]
	v_pk_fma_f32 v[50:51], v[50:51], v[68:69], v[130:131] op_sel_hi:[1,0,1]
	v_max_f32_e32 v52, 0, v52
	v_max_f32_e32 v48, 0, v48
	v_max_f32_e32 v53, 0, v53
	v_max_f32_e32 v49, 0, v49
	global_store_dwordx4 v[60:61], v[56:59], off nt
	v_pk_mul_f32 v[52:53], v[52:53], v[52:53]
	v_max_f32_e32 v50, 0, v50
	v_pk_mul_f32 v[56:57], v[48:49], v[48:49]
	v_max_f32_e32 v48, 0, v54
	v_max_f32_e32 v49, 0, v55
	v_max_f32_e32 v51, 0, v51
	v_pk_mul_f32 v[54:55], v[48:49], v[48:49]
	v_pk_mul_f32 v[58:59], v[50:51], v[50:51]
	v_cvt_pk_bf16_f32 v48, v52, v53
	v_add_co_u32_e32 v52, vcc, s50, v160
	v_cvt_pk_bf16_f32 v49, v54, v55
	v_cvt_pk_bf16_f32 v50, v56, v57
	v_cvt_pk_bf16_f32 v51, v58, v59
	v_addc_co_u32_e32 v53, vcc, 0, v161, vcc
	global_store_dwordx4 v[52:53], v[48:51], off nt
	s_andn2_b64 vcc, exec, s[4:5]
	s_mov_b64 s[4:5], -1
	v_mov_b32_e32 v48, v69
	v_pk_fma_f32 v[40:41], v[40:41], v[48:49], v[136:137] op_sel_hi:[1,0,1]
	v_pk_fma_f32 v[46:47], v[46:47], v[48:49], v[142:143] op_sel_hi:[1,0,1]
	v_pk_fma_f32 v[44:45], v[44:45], v[48:49], v[140:141] op_sel_hi:[1,0,1]
	v_pk_fma_f32 v[42:43], v[42:43], v[48:49], v[138:139] op_sel_hi:[1,0,1]
	v_max_f32_e32 v40, 0, v40
	v_max_f32_e32 v41, 0, v41
	v_max_f32_e32 v44, 0, v44
	v_max_f32_e32 v45, 0, v45
	v_pk_mul_f32 v[50:51], v[40:41], v[40:41]
	v_max_f32_e32 v40, 0, v46
	v_max_f32_e32 v42, 0, v42
	v_max_f32_e32 v41, 0, v47
	v_max_f32_e32 v43, 0, v43
	v_pk_mul_f32 v[44:45], v[44:45], v[44:45]
	v_pk_mul_f32 v[46:47], v[40:41], v[40:41]
	v_pk_mul_f32 v[54:55], v[42:43], v[42:43]
	v_pk_fma_f32 v[36:37], v[36:37], v[48:49], v[132:133] op_sel_hi:[1,0,1]
	v_pk_fma_f32 v[32:33], v[32:33], v[48:49], v[128:129] op_sel_hi:[1,0,1]
	v_cvt_pk_bf16_f32 v40, v44, v45
	v_cvt_pk_bf16_f32 v41, v46, v47
	v_cvt_pk_bf16_f32 v42, v50, v51
	v_cvt_pk_bf16_f32 v43, v54, v55
	v_pk_fma_f32 v[38:39], v[38:39], v[48:49], v[134:135] op_sel_hi:[1,0,1]
	v_max_f32_e32 v36, 0, v36
	v_max_f32_e32 v32, 0, v32
	v_max_f32_e32 v37, 0, v37
	v_max_f32_e32 v33, 0, v33
	global_store_dwordx4 v[60:61], v[40:43], off offset:1024 nt
	v_pk_mul_f32 v[36:37], v[36:37], v[36:37]
	v_pk_fma_f32 v[34:35], v[34:35], v[48:49], v[130:131] op_sel_hi:[1,0,1]
	v_pk_mul_f32 v[40:41], v[32:33], v[32:33]
	v_max_f32_e32 v32, 0, v38
	v_max_f32_e32 v33, 0, v39
	v_pk_mul_f32 v[38:39], v[32:33], v[32:33]
	v_cvt_pk_bf16_f32 v32, v36, v37
	ds_read2_b32 v[36:37], v170 offset0:160 offset1:176
	v_max_f32_e32 v34, 0, v34
	v_max_f32_e32 v35, 0, v35
	v_pk_mul_f32 v[42:43], v[34:35], v[34:35]
	v_cvt_pk_bf16_f32 v33, v38, v39
	s_waitcnt lgkmcnt(0)
	v_pk_fma_f32 v[24:25], v[24:25], v[36:37], v[136:137] op_sel_hi:[1,0,1]
	v_cvt_pk_bf16_f32 v34, v40, v41
	v_cvt_pk_bf16_f32 v35, v42, v43
	v_pk_fma_f32 v[30:31], v[30:31], v[36:37], v[142:143] op_sel_hi:[1,0,1]
	v_pk_fma_f32 v[28:29], v[28:29], v[36:37], v[140:141] op_sel_hi:[1,0,1]
	v_pk_fma_f32 v[26:27], v[26:27], v[36:37], v[138:139] op_sel_hi:[1,0,1]
	v_max_f32_e32 v24, 0, v24
	v_max_f32_e32 v25, 0, v25
	global_store_dwordx4 v[52:53], v[32:35], off offset:1024 nt
	v_max_f32_e32 v28, 0, v28
	v_max_f32_e32 v29, 0, v29
	v_pk_mul_f32 v[32:33], v[24:25], v[24:25]
	v_max_f32_e32 v24, 0, v30
	v_max_f32_e32 v26, 0, v26
	v_max_f32_e32 v25, 0, v31
	v_max_f32_e32 v27, 0, v27
	v_pk_mul_f32 v[28:29], v[28:29], v[28:29]
	v_pk_mul_f32 v[30:31], v[24:25], v[24:25]
	v_pk_mul_f32 v[34:35], v[26:27], v[26:27]
	v_pk_fma_f32 v[16:17], v[16:17], v[36:37], v[128:129] op_sel_hi:[1,0,1]
	v_cvt_pk_bf16_f32 v24, v28, v29
	v_cvt_pk_bf16_f32 v25, v30, v31
	v_cvt_pk_bf16_f32 v26, v32, v33
	v_cvt_pk_bf16_f32 v27, v34, v35
	v_pk_fma_f32 v[22:23], v[22:23], v[36:37], v[134:135] op_sel_hi:[1,0,1]
	v_pk_fma_f32 v[20:21], v[20:21], v[36:37], v[132:133] op_sel_hi:[1,0,1]
	v_pk_fma_f32 v[18:19], v[18:19], v[36:37], v[130:131] op_sel_hi:[1,0,1]
	v_max_f32_e32 v16, 0, v16
	v_max_f32_e32 v17, 0, v17
	global_store_dwordx4 v[60:61], v[24:27], off offset:2048 nt
	v_max_f32_e32 v20, 0, v20
	v_max_f32_e32 v21, 0, v21
	v_pk_mul_f32 v[24:25], v[16:17], v[16:17]
	v_max_f32_e32 v16, 0, v22
	v_max_f32_e32 v18, 0, v18
	v_max_f32_e32 v17, 0, v23
	v_max_f32_e32 v19, 0, v19
	v_pk_mul_f32 v[20:21], v[20:21], v[20:21]
	v_pk_mul_f32 v[22:23], v[16:17], v[16:17]
	v_pk_mul_f32 v[26:27], v[18:19], v[18:19]
	v_cvt_pk_bf16_f32 v16, v20, v21
	v_cvt_pk_bf16_f32 v17, v22, v23
	v_cvt_pk_bf16_f32 v18, v24, v25
	v_cvt_pk_bf16_f32 v19, v26, v27
	global_store_dwordx4 v[52:53], v[16:19], off offset:2048 nt
	s_nop 1
	v_mov_b32_e32 v16, v37
	v_pk_fma_f32 v[8:9], v[8:9], v[16:17], v[136:137] op_sel_hi:[1,0,1]
	v_pk_fma_f32 v[14:15], v[14:15], v[16:17], v[142:143] op_sel_hi:[1,0,1]
	v_pk_fma_f32 v[12:13], v[12:13], v[16:17], v[140:141] op_sel_hi:[1,0,1]
	v_pk_fma_f32 v[10:11], v[10:11], v[16:17], v[138:139] op_sel_hi:[1,0,1]
	v_max_f32_e32 v8, 0, v8
	v_max_f32_e32 v9, 0, v9
	v_max_f32_e32 v12, 0, v12
	v_max_f32_e32 v13, 0, v13
	v_pk_mul_f32 v[18:19], v[8:9], v[8:9]
	v_max_f32_e32 v8, 0, v14
	v_max_f32_e32 v10, 0, v10
	v_max_f32_e32 v9, 0, v15
	v_max_f32_e32 v11, 0, v11
	v_pk_mul_f32 v[12:13], v[12:13], v[12:13]
	v_pk_mul_f32 v[14:15], v[8:9], v[8:9]
	v_pk_mul_f32 v[20:21], v[10:11], v[10:11]
	v_pk_fma_f32 v[0:1], v[0:1], v[16:17], v[128:129] op_sel_hi:[1,0,1]
	v_cvt_pk_bf16_f32 v8, v12, v13
	v_cvt_pk_bf16_f32 v9, v14, v15
	v_cvt_pk_bf16_f32 v10, v18, v19
	v_cvt_pk_bf16_f32 v11, v20, v21
	v_pk_fma_f32 v[6:7], v[6:7], v[16:17], v[134:135] op_sel_hi:[1,0,1]
	v_pk_fma_f32 v[4:5], v[4:5], v[16:17], v[132:133] op_sel_hi:[1,0,1]
	v_pk_fma_f32 v[2:3], v[2:3], v[16:17], v[130:131] op_sel_hi:[1,0,1]
	v_max_f32_e32 v0, 0, v0
	v_max_f32_e32 v1, 0, v1
	global_store_dwordx4 v[60:61], v[8:11], off offset:3072 nt
	v_max_f32_e32 v4, 0, v4
	v_max_f32_e32 v5, 0, v5
	v_pk_mul_f32 v[8:9], v[0:1], v[0:1]
	v_max_f32_e32 v0, 0, v6
	v_max_f32_e32 v2, 0, v2
	v_max_f32_e32 v1, 0, v7
	v_max_f32_e32 v3, 0, v3
	v_pk_mul_f32 v[4:5], v[4:5], v[4:5]
	v_pk_mul_f32 v[6:7], v[0:1], v[0:1]
	v_pk_mul_f32 v[10:11], v[2:3], v[2:3]
	v_cvt_pk_bf16_f32 v0, v4, v5
	v_cvt_pk_bf16_f32 v1, v6, v7
	v_cvt_pk_bf16_f32 v2, v8, v9
	v_cvt_pk_bf16_f32 v3, v10, v11
	global_store_dwordx4 v[52:53], v[0:3], off offset:3072 nt
	s_cbranch_vccnz .LBB0_560
	s_andn2_b64 vcc, exec, s[8:9]
	s_cbranch_vccnz .LBB0_559
	s_barrier
	s_branch .LBB0_559

.LBB0_659:
	v_add_u32_e32 v188, s14, v214
	v_readlane_b32 s4, v251, 2
	v_add_u32_e32 v190, 16, v188
	v_readlane_b32 s18, v251, 16
	v_readlane_b32 s19, v251, 17
	v_ashrrev_i32_e32 v189, 31, v188
	v_ashrrev_i32_e32 v191, 31, v190
	v_add_u32_e32 v174, 32, v188
	v_add_u32_e32 v172, 48, v188
	v_lshl_add_u64 v[4:5], s[18:19], 0, v[212:213]
	v_lshl_add_u64 v[16:17], v[188:189], 4, s[0:1]
	v_lshl_add_u64 v[18:19], v[190:191], 4, s[0:1]
	v_ashrrev_i32_e32 v175, 31, v174
	v_ashrrev_i32_e32 v173, 31, v172
	v_add_u32_e32 v146, 0x80, v188
	v_add_u32_e32 v144, 0x90, v188
	s_barrier
	global_load_dwordx4 v[8:11], v[4:5], off offset:16
	global_load_dwordx4 v[12:15], v[4:5], off
	global_load_dwordx4 v[0:3], v[4:5], off offset:528
	s_nop 0
	global_load_dwordx4 v[4:7], v[4:5], off offset:512
	s_nop 0
	global_load_dwordx4 v[176:179], v[16:17], off
	global_load_dwordx4 v[180:183], v[18:19], off
	v_lshl_add_u64 v[16:17], v[174:175], 4, s[0:1]
	v_lshl_add_u64 v[18:19], v[172:173], 4, s[0:1]
	v_ashrrev_i32_e32 v147, 31, v146
	v_ashrrev_i32_e32 v145, 31, v144
	v_add_u32_e32 v142, 0xa0, v188
	v_add_u32_e32 v140, 0xb0, v188
	global_load_dwordx4 v[184:187], v[16:17], off
	global_load_dwordx4 v[32:35], v[18:19], off
	v_lshl_add_u64 v[16:17], v[146:147], 4, s[0:1]
	v_lshl_add_u64 v[18:19], v[144:145], 4, s[0:1]
	v_ashrrev_i32_e32 v143, 31, v142
	v_ashrrev_i32_e32 v141, 31, v140
	global_load_dwordx4 v[28:31], v[16:17], off
	global_load_dwordx4 v[24:27], v[18:19], off
	v_lshl_add_u64 v[16:17], v[142:143], 4, s[0:1]
	v_lshl_add_u64 v[18:19], v[140:141], 4, s[0:1]
	global_load_dwordx4 v[20:23], v[16:17], off
	s_nop 0
	global_load_dwordx4 v[16:19], v[18:19], off
	v_readlane_b32 s5, v251, 3
	v_readlane_b32 s6, v251, 4
	v_readlane_b32 s7, v251, 5
	v_readlane_b32 s8, v251, 6
	v_readlane_b32 s9, v251, 7
	v_readlane_b32 s10, v251, 8
	v_readlane_b32 s11, v251, 9
	v_readlane_b32 s12, v251, 10
	v_readlane_b32 s13, v251, 11
	v_readlane_b32 s14, v251, 12
	v_readlane_b32 s15, v251, 13
	v_readlane_b32 s16, v251, 14
	v_readlane_b32 s17, v251, 15
	s_waitcnt vmcnt(7)
	v_mov_b32_e32 v192, v177
	v_mov_b32_e32 v193, v178
	v_mov_b32_e32 v177, v179
	v_pk_add_f32 v[176:177], v[192:193], v[176:177]
	s_mov_b32 s2, 0xf800000
	v_add_f32_e32 v177, v176, v177
	v_mov_b32_e32 v176, 0x358637bd
	v_fmamk_f32 v177, v177, 0x3a800000, v176
	v_mul_f32_e32 v178, 0x4f800000, v177
	v_cmp_gt_f32_e32 vcc, s2, v177
	v_lshlrev_b64 v[188:189], 12, v[188:189]
	v_lshl_add_u64 v[188:189], s[52:53], 0, v[188:189]
	v_cndmask_b32_e32 v178, v177, v178, vcc
	v_sqrt_f32_e32 v177, v178
	v_lshl_add_u64 v[188:189], v[188:189], 0, v[212:213]
	v_add_u32_e32 v179, -1, v177
	v_fma_f32 v192, -v179, v177, v178
	v_cmp_ge_f32_e64 s[0:1], 0, v192
	v_add_u32_e32 v192, 1, v177
	s_nop 0
	v_cndmask_b32_e64 v179, v177, v179, s[0:1]
	v_fma_f32 v177, -v192, v177, v178
	v_cmp_lt_f32_e64 s[0:1], 0, v177
	s_nop 1
	v_cndmask_b32_e64 v177, v179, v192, s[0:1]
	v_mul_f32_e32 v179, 0x37800000, v177
	v_cndmask_b32_e32 v179, v177, v179, vcc
	v_mov_b32_e32 v177, 0x260
	v_cmp_class_f32_e32 vcc, v178, v177
	s_nop 1
	v_cndmask_b32_e32 v178, v179, v178, vcc
	v_div_scale_f32 v179, s[0:1], v178, v178, 1.0
	v_rcp_f32_e32 v192, v179
	s_nop 0
	v_fma_f32 v193, -v179, v192, 1.0
	v_fmac_f32_e32 v192, v193, v192
	v_div_scale_f32 v193, vcc, 1.0, v178, 1.0
	v_mul_f32_e32 v194, v193, v192
	v_fma_f32 v195, -v179, v194, v193
	v_fmac_f32_e32 v194, v195, v192
	v_fma_f32 v179, -v179, v194, v193
	v_div_fmas_f32 v179, v179, v192, v194
	v_div_fixup_f32 v178, v179, v178, 1.0
	v_pk_mul_f32 v[120:121], v[120:121], v[178:179] op_sel_hi:[1,0]
	v_pk_mul_f32 v[122:123], v[122:123], v[178:179] op_sel_hi:[1,0]
	v_pk_mul_f32 v[120:121], v[8:9], v[120:121]
	v_pk_mul_f32 v[122:123], v[10:11], v[122:123]
	global_store_dwordx4 v[188:189], v[120:123], off offset:16 nt
	v_pk_mul_f32 v[116:117], v[116:117], v[178:179] op_sel_hi:[1,0]
	v_pk_mul_f32 v[118:119], v[118:119], v[178:179] op_sel_hi:[1,0]
	s_waitcnt vmcnt(7)
	v_mov_b32_e32 v120, v181
	v_mov_b32_e32 v121, v182
	v_mov_b32_e32 v181, v183
	v_pk_add_f32 v[120:121], v[120:121], v[180:181]
	v_pk_mul_f32 v[118:119], v[6:7], v[118:119]
	v_add_f32_e32 v120, v120, v121
	v_fmamk_f32 v120, v120, 0x3a800000, v176
	v_mul_f32_e32 v121, 0x4f800000, v120
	v_cmp_gt_f32_e32 vcc, s2, v120
	v_pk_mul_f32 v[116:117], v[4:5], v[116:117]
	global_store_dwordx4 v[188:189], v[116:119], off offset:512 nt
	v_cndmask_b32_e32 v120, v120, v121, vcc
	v_sqrt_f32_e32 v121, v120
	v_pk_mul_f32 v[112:113], v[112:113], v[178:179] op_sel_hi:[1,0]
	v_pk_mul_f32 v[114:115], v[114:115], v[178:179] op_sel_hi:[1,0]
	v_pk_mul_f32 v[112:113], v[0:1], v[112:113]
	v_add_u32_e32 v116, -1, v121
	v_fma_f32 v117, -v116, v121, v120
	v_cmp_ge_f32_e64 s[0:1], 0, v117
	v_add_u32_e32 v117, 1, v121
	v_fma_f32 v118, -v117, v121, v120
	v_cndmask_b32_e64 v116, v121, v116, s[0:1]
	v_cmp_lt_f32_e64 s[0:1], 0, v118
	v_pk_mul_f32 v[114:115], v[2:3], v[114:115]
	global_store_dwordx4 v[188:189], v[112:115], off offset:528 nt
	v_cndmask_b32_e64 v116, v116, v117, s[0:1]
	v_mul_f32_e32 v117, 0x37800000, v116
	v_cndmask_b32_e32 v116, v116, v117, vcc
	v_cmp_class_f32_e32 vcc, v120, v177
	v_pk_mul_f32 v[124:125], v[124:125], v[178:179] op_sel_hi:[1,0]
	v_pk_mul_f32 v[126:127], v[126:127], v[178:179] op_sel_hi:[1,0]
	v_cndmask_b32_e32 v116, v116, v120, vcc
	v_div_scale_f32 v117, s[0:1], v116, v116, 1.0
	v_rcp_f32_e32 v118, v117
	v_pk_mul_f32 v[124:125], v[12:13], v[124:125]
	v_pk_mul_f32 v[126:127], v[14:15], v[126:127]
	global_store_dwordx4 v[188:189], v[124:127], off nt
	v_fma_f32 v112, -v117, v118, 1.0
	v_fmac_f32_e32 v118, v112, v118
	v_div_scale_f32 v112, vcc, 1.0, v116, 1.0
	v_mul_f32_e32 v113, v112, v118
	v_fma_f32 v114, -v117, v113, v112
	v_fmac_f32_e32 v113, v114, v118
	v_fma_f32 v112, -v117, v113, v112
	v_div_fmas_f32 v112, v112, v118, v113
	v_div_fixup_f32 v112, v112, v116, 1.0
	v_lshlrev_b64 v[114:115], 12, v[190:191]
	v_lshl_add_u64 v[114:115], s[52:53], 0, v[114:115]
	v_pk_mul_f32 v[104:105], v[104:105], v[112:113] op_sel_hi:[1,0]
	v_pk_mul_f32 v[106:107], v[106:107], v[112:113] op_sel_hi:[1,0]
	v_lshl_add_u64 v[114:115], v[114:115], 0, v[212:213]
	v_pk_mul_f32 v[106:107], v[10:11], v[106:107]
	v_pk_mul_f32 v[104:105], v[8:9], v[104:105]
	global_store_dwordx4 v[114:115], v[104:107], off offset:16 nt
	v_pk_mul_f32 v[100:101], v[100:101], v[112:113] op_sel_hi:[1,0]
	v_pk_mul_f32 v[102:103], v[102:103], v[112:113] op_sel_hi:[1,0]
	s_waitcnt vmcnt(10)
	v_mov_b32_e32 v104, v185
	v_mov_b32_e32 v105, v186
	v_mov_b32_e32 v185, v187
	v_pk_add_f32 v[104:105], v[104:105], v[184:185]
	v_pk_mul_f32 v[102:103], v[6:7], v[102:103]
	v_add_f32_e32 v104, v104, v105
	v_fmamk_f32 v104, v104, 0x3a800000, v176
	v_mul_f32_e32 v105, 0x4f800000, v104
	v_cmp_gt_f32_e32 vcc, s2, v104
	v_pk_mul_f32 v[100:101], v[4:5], v[100:101]
	global_store_dwordx4 v[114:115], v[100:103], off offset:512 nt
	v_cndmask_b32_e32 v104, v104, v105, vcc
	v_sqrt_f32_e32 v105, v104
	v_pk_mul_f32 v[96:97], v[96:97], v[112:113] op_sel_hi:[1,0]
	v_pk_mul_f32 v[98:99], v[98:99], v[112:113] op_sel_hi:[1,0]
	v_pk_mul_f32 v[96:97], v[0:1], v[96:97]
	v_add_u32_e32 v100, -1, v105
	v_fma_f32 v101, -v100, v105, v104
	v_cmp_ge_f32_e64 s[0:1], 0, v101
	v_add_u32_e32 v101, 1, v105
	v_fma_f32 v102, -v101, v105, v104
	v_cndmask_b32_e64 v100, v105, v100, s[0:1]
	v_cmp_lt_f32_e64 s[0:1], 0, v102
	v_pk_mul_f32 v[98:99], v[2:3], v[98:99]
	global_store_dwordx4 v[114:115], v[96:99], off offset:528 nt
	v_cndmask_b32_e64 v100, v100, v101, s[0:1]
	v_mul_f32_e32 v101, 0x37800000, v100
	v_cndmask_b32_e32 v100, v100, v101, vcc
	v_cmp_class_f32_e32 vcc, v104, v177
	v_pk_mul_f32 v[108:109], v[108:109], v[112:113] op_sel_hi:[1,0]
	v_pk_mul_f32 v[110:111], v[110:111], v[112:113] op_sel_hi:[1,0]
	v_cndmask_b32_e32 v100, v100, v104, vcc
	v_div_scale_f32 v101, s[0:1], v100, v100, 1.0
	v_rcp_f32_e32 v102, v101
	v_pk_mul_f32 v[108:109], v[12:13], v[108:109]
	v_pk_mul_f32 v[110:111], v[14:15], v[110:111]
	global_store_dwordx4 v[114:115], v[108:111], off nt
	v_fma_f32 v96, -v101, v102, 1.0
	v_fmac_f32_e32 v102, v96, v102
	v_div_scale_f32 v96, vcc, 1.0, v100, 1.0
	v_mul_f32_e32 v97, v96, v102
	v_fma_f32 v98, -v101, v97, v96
	v_fmac_f32_e32 v97, v98, v102
	v_fma_f32 v96, -v101, v97, v96
	v_div_fmas_f32 v96, v96, v102, v97
	v_div_fixup_f32 v96, v96, v100, 1.0
	v_lshlrev_b64 v[98:99], 12, v[174:175]
	v_lshl_add_u64 v[98:99], s[52:53], 0, v[98:99]
	v_pk_mul_f32 v[88:89], v[88:89], v[96:97] op_sel_hi:[1,0]
	v_pk_mul_f32 v[90:91], v[90:91], v[96:97] op_sel_hi:[1,0]
	v_lshl_add_u64 v[98:99], v[98:99], 0, v[212:213]
	v_pk_mul_f32 v[90:91], v[10:11], v[90:91]
	v_pk_mul_f32 v[88:89], v[8:9], v[88:89]
	global_store_dwordx4 v[98:99], v[88:91], off offset:16 nt
	v_pk_mul_f32 v[92:93], v[92:93], v[96:97] op_sel_hi:[1,0]
	v_pk_mul_f32 v[94:95], v[94:95], v[96:97] op_sel_hi:[1,0]
	s_waitcnt vmcnt(13)
	v_mov_b32_e32 v88, v33
	v_mov_b32_e32 v89, v34
	v_mov_b32_e32 v33, v35
	v_pk_add_f32 v[32:33], v[88:89], v[32:33]
	v_pk_mul_f32 v[34:35], v[82:83], v[96:97] op_sel_hi:[1,0]
	v_add_f32_e32 v32, v32, v33
	v_fmamk_f32 v32, v32, 0x3a800000, v176
	v_mul_f32_e32 v33, 0x4f800000, v32
	v_cmp_gt_f32_e32 vcc, s2, v32
	v_pk_mul_f32 v[34:35], v[2:3], v[34:35]
	v_pk_mul_f32 v[92:93], v[12:13], v[92:93]
	v_cndmask_b32_e32 v88, v32, v33, vcc
	v_sqrt_f32_e32 v89, v88
	v_pk_mul_f32 v[32:33], v[80:81], v[96:97] op_sel_hi:[1,0]
	v_pk_mul_f32 v[94:95], v[14:15], v[94:95]
	v_pk_mul_f32 v[32:33], v[0:1], v[32:33]
	v_add_u32_e32 v80, -1, v89
	v_fma_f32 v81, -v80, v89, v88
	v_cmp_ge_f32_e64 s[0:1], 0, v81
	v_add_u32_e32 v81, 1, v89
	v_fma_f32 v82, -v81, v89, v88
	v_cndmask_b32_e64 v80, v89, v80, s[0:1]
	v_cmp_lt_f32_e64 s[0:1], 0, v82
	global_store_dwordx4 v[98:99], v[32:35], off offset:528 nt
	v_pk_mul_f32 v[84:85], v[84:85], v[96:97] op_sel_hi:[1,0]
	v_cndmask_b32_e64 v80, v80, v81, s[0:1]
	v_mul_f32_e32 v81, 0x37800000, v80
	v_cndmask_b32_e32 v80, v80, v81, vcc
	v_cmp_class_f32_e32 vcc, v88, v177
	v_pk_mul_f32 v[86:87], v[86:87], v[96:97] op_sel_hi:[1,0]
	v_pk_mul_f32 v[84:85], v[4:5], v[84:85]
	v_cndmask_b32_e32 v80, v80, v88, vcc
	v_div_scale_f32 v81, s[0:1], v80, v80, 1.0
	v_rcp_f32_e32 v82, v81
	v_pk_mul_f32 v[86:87], v[6:7], v[86:87]
	global_store_dwordx4 v[98:99], v[92:95], off nt
	global_store_dwordx4 v[98:99], v[84:87], off offset:512 nt
	v_fma_f32 v32, -v81, v82, 1.0
	v_fmac_f32_e32 v82, v32, v82
	v_div_scale_f32 v32, vcc, 1.0, v80, 1.0
	v_mul_f32_e32 v33, v32, v82
	v_fma_f32 v34, -v81, v33, v32
	v_fmac_f32_e32 v33, v34, v82
	v_fma_f32 v32, -v81, v33, v32
	v_div_fmas_f32 v32, v32, v82, v33
	v_div_fixup_f32 v80, v32, v80, 1.0
	v_pk_mul_f32 v[32:33], v[76:77], v[80:81] op_sel_hi:[1,0]
	v_lshlrev_b64 v[76:77], 12, v[172:173]
	v_pk_mul_f32 v[34:35], v[78:79], v[80:81] op_sel_hi:[1,0]
	v_lshl_add_u64 v[76:77], s[52:53], 0, v[76:77]
	v_pk_mul_f32 v[34:35], v[14:15], v[34:35]
	v_pk_mul_f32 v[32:33], v[12:13], v[32:33]
	v_lshl_add_u64 v[76:77], v[76:77], 0, v[212:213]
	global_store_dwordx4 v[76:77], v[32:35], off nt
	s_nop 1
	v_pk_mul_f32 v[32:33], v[72:73], v[80:81] op_sel_hi:[1,0]
	v_pk_mul_f32 v[34:35], v[74:75], v[80:81] op_sel_hi:[1,0]
	v_pk_mul_f32 v[32:33], v[8:9], v[32:33]
	v_pk_mul_f32 v[34:35], v[10:11], v[34:35]
	global_store_dwordx4 v[76:77], v[32:35], off offset:16 nt
	s_nop 1
	v_pk_mul_f32 v[32:33], v[68:69], v[80:81] op_sel_hi:[1,0]
	s_waitcnt vmcnt(17)
	v_mov_b32_e32 v68, v29
	v_mov_b32_e32 v69, v30
	v_mov_b32_e32 v29, v31
	v_pk_add_f32 v[28:29], v[68:69], v[28:29]
	v_pk_mul_f32 v[34:35], v[70:71], v[80:81] op_sel_hi:[1,0]
	v_add_f32_e32 v28, v28, v29
	v_fmamk_f32 v28, v28, 0x3a800000, v176
	v_mul_f32_e32 v29, 0x4f800000, v28
	v_cmp_gt_f32_e32 vcc, s2, v28
	v_pk_mul_f32 v[34:35], v[6:7], v[34:35]
	v_pk_mul_f32 v[32:33], v[4:5], v[32:33]
	v_cndmask_b32_e32 v68, v28, v29, vcc
	v_sqrt_f32_e32 v69, v68
	global_store_dwordx4 v[76:77], v[32:35], off offset:512 nt
	v_pk_mul_f32 v[28:29], v[64:65], v[80:81] op_sel_hi:[1,0]
	v_pk_mul_f32 v[30:31], v[66:67], v[80:81] op_sel_hi:[1,0]
	v_add_u32_e32 v32, -1, v69
	v_fma_f32 v33, -v32, v69, v68
	v_cmp_ge_f32_e64 s[0:1], 0, v33
	v_add_u32_e32 v33, 1, v69
	v_fma_f32 v34, -v33, v69, v68
	v_cndmask_b32_e64 v32, v69, v32, s[0:1]
	v_cmp_lt_f32_e64 s[0:1], 0, v34
	v_pk_mul_f32 v[30:31], v[2:3], v[30:31]
	v_pk_mul_f32 v[28:29], v[0:1], v[28:29]
	v_cndmask_b32_e64 v32, v32, v33, s[0:1]
	v_mul_f32_e32 v33, 0x37800000, v32
	v_cndmask_b32_e32 v32, v32, v33, vcc
	v_cmp_class_f32_e32 vcc, v68, v177
	global_store_dwordx4 v[76:77], v[28:31], off offset:528 nt
	s_nop 0
	v_cndmask_b32_e32 v32, v32, v68, vcc
	v_div_scale_f32 v33, s[0:1], v32, v32, 1.0
	v_rcp_f32_e32 v34, v33
	s_nop 0
	v_fma_f32 v28, -v33, v34, 1.0
	v_fmac_f32_e32 v34, v28, v34
	v_div_scale_f32 v28, vcc, 1.0, v32, 1.0
	v_mul_f32_e32 v29, v28, v34
	v_fma_f32 v30, -v33, v29, v28
	v_fmac_f32_e32 v29, v30, v34
	v_fma_f32 v28, -v33, v29, v28
	v_div_fmas_f32 v28, v28, v34, v29
	v_div_fixup_f32 v32, v28, v32, 1.0
	v_lshlrev_b64 v[34:35], 12, v[146:147]
	v_pk_mul_f32 v[28:29], v[60:61], v[32:33] op_sel_hi:[1,0]
	v_pk_mul_f32 v[30:31], v[62:63], v[32:33] op_sel_hi:[1,0]
	v_lshl_add_u64 v[34:35], s[52:53], 0, v[34:35]
	v_pk_mul_f32 v[30:31], v[14:15], v[30:31]
	v_pk_mul_f32 v[28:29], v[12:13], v[28:29]
	v_lshl_add_u64 v[34:35], v[34:35], 0, v[212:213]
	global_store_dwordx4 v[34:35], v[28:31], off nt
	s_nop 1
	v_pk_mul_f32 v[28:29], v[56:57], v[32:33] op_sel_hi:[1,0]
	s_waitcnt vmcnt(19)
	v_mov_b32_e32 v56, v25
	v_mov_b32_e32 v57, v26
	v_mov_b32_e32 v25, v27
	v_pk_add_f32 v[24:25], v[56:57], v[24:25]
	v_pk_mul_f32 v[30:31], v[58:59], v[32:33] op_sel_hi:[1,0]
	v_add_f32_e32 v24, v24, v25
	v_fmamk_f32 v24, v24, 0x3a800000, v176
	v_pk_mul_f32 v[30:31], v[10:11], v[30:31]
	v_pk_mul_f32 v[28:29], v[8:9], v[28:29]
	v_mul_f32_e32 v25, 0x4f800000, v24
	v_cmp_gt_f32_e32 vcc, s2, v24
	global_store_dwordx4 v[34:35], v[28:31], off offset:16 nt
	s_nop 1
	v_pk_mul_f32 v[28:29], v[170:171], v[32:33] op_sel_hi:[1,0]
	v_pk_mul_f32 v[30:31], v[168:169], v[32:33] op_sel_hi:[1,0]
	v_cndmask_b32_e32 v33, v24, v25, vcc
	v_sqrt_f32_e32 v56, v33
	v_pk_mul_f32 v[30:31], v[6:7], v[30:31]
	v_pk_mul_f32 v[28:29], v[4:5], v[28:29]
	global_store_dwordx4 v[34:35], v[28:31], off offset:512 nt
	v_pk_mul_f32 v[24:25], v[48:49], v[32:33] op_sel_hi:[1,0]
	v_pk_mul_f32 v[26:27], v[50:51], v[32:33] op_sel_hi:[1,0]
	v_add_u32_e32 v28, -1, v56
	v_fma_f32 v29, -v28, v56, v33
	v_cmp_ge_f32_e64 s[0:1], 0, v29
	v_add_u32_e32 v29, 1, v56
	v_fma_f32 v30, -v29, v56, v33
	v_cndmask_b32_e64 v28, v56, v28, s[0:1]
	v_cmp_lt_f32_e64 s[0:1], 0, v30
	v_pk_mul_f32 v[26:27], v[2:3], v[26:27]
	v_pk_mul_f32 v[24:25], v[0:1], v[24:25]
	v_cndmask_b32_e64 v28, v28, v29, s[0:1]
	v_mul_f32_e32 v29, 0x37800000, v28
	v_cndmask_b32_e32 v28, v28, v29, vcc
	v_cmp_class_f32_e32 vcc, v33, v177
	global_store_dwordx4 v[34:35], v[24:27], off offset:528 nt
	s_waitcnt vmcnt(21)
	v_mov_b32_e32 v32, v21
	v_cndmask_b32_e32 v28, v28, v33, vcc
	v_div_scale_f32 v29, s[0:1], v28, v28, 1.0
	v_rcp_f32_e32 v30, v29
	v_mov_b32_e32 v33, v22
	v_mov_b32_e32 v21, v23
	v_pk_add_f32 v[20:21], v[32:33], v[20:21]
	v_fma_f32 v24, -v29, v30, 1.0
	v_fmac_f32_e32 v30, v24, v30
	v_div_scale_f32 v24, vcc, 1.0, v28, 1.0
	v_mul_f32_e32 v25, v24, v30
	v_fma_f32 v26, -v29, v25, v24
	v_fmac_f32_e32 v25, v26, v30
	v_fma_f32 v24, -v29, v25, v24
	v_div_fmas_f32 v24, v24, v30, v25
	v_div_fixup_f32 v28, v24, v28, 1.0
	v_lshlrev_b64 v[30:31], 12, v[144:145]
	v_pk_mul_f32 v[24:25], v[52:53], v[28:29] op_sel_hi:[1,0]
	v_pk_mul_f32 v[26:27], v[46:47], v[28:29] op_sel_hi:[1,0]
	v_lshl_add_u64 v[30:31], s[52:53], 0, v[30:31]
	v_pk_mul_f32 v[26:27], v[14:15], v[26:27]
	v_pk_mul_f32 v[24:25], v[12:13], v[24:25]
	v_lshl_add_u64 v[30:31], v[30:31], 0, v[212:213]
	v_add_f32_e32 v20, v20, v21
	global_store_dwordx4 v[30:31], v[24:27], off nt
	v_fmamk_f32 v20, v20, 0x3a800000, v176
	v_mul_f32_e32 v21, 0x4f800000, v20
	v_pk_mul_f32 v[24:25], v[40:41], v[28:29] op_sel_hi:[1,0]
	v_pk_mul_f32 v[26:27], v[42:43], v[28:29] op_sel_hi:[1,0]
	v_pk_mul_f32 v[24:25], v[8:9], v[24:25]
	v_pk_mul_f32 v[26:27], v[10:11], v[26:27]
	v_cmp_gt_f32_e32 vcc, s2, v20
	global_store_dwordx4 v[30:31], v[24:27], off offset:16 nt
	s_nop 1
	v_pk_mul_f32 v[24:25], v[164:165], v[28:29] op_sel_hi:[1,0]
	v_pk_mul_f32 v[26:27], v[162:163], v[28:29] op_sel_hi:[1,0]
	v_cndmask_b32_e32 v29, v20, v21, vcc
	v_sqrt_f32_e32 v32, v29
	v_pk_mul_f32 v[26:27], v[6:7], v[26:27]
	v_pk_mul_f32 v[24:25], v[4:5], v[24:25]
	global_store_dwordx4 v[30:31], v[24:27], off offset:512 nt
	v_pk_mul_f32 v[20:21], v[38:39], v[28:29] op_sel_hi:[1,0]
	v_pk_mul_f32 v[22:23], v[36:37], v[28:29] op_sel_hi:[1,0]
	v_add_u32_e32 v24, -1, v32
	v_fma_f32 v25, -v24, v32, v29
	v_cmp_ge_f32_e64 s[0:1], 0, v25
	v_add_u32_e32 v25, 1, v32
	v_fma_f32 v26, -v25, v32, v29
	v_cndmask_b32_e64 v24, v32, v24, s[0:1]
	v_cmp_lt_f32_e64 s[0:1], 0, v26
	v_pk_mul_f32 v[22:23], v[2:3], v[22:23]
	v_pk_mul_f32 v[20:21], v[0:1], v[20:21]
	v_cndmask_b32_e64 v24, v24, v25, s[0:1]
	v_mul_f32_e32 v25, 0x37800000, v24
	v_cndmask_b32_e32 v24, v24, v25, vcc
	v_cmp_class_f32_e32 vcc, v29, v177
	global_store_dwordx4 v[30:31], v[20:23], off offset:528 nt
	s_waitcnt vmcnt(24)
	v_mov_b32_e32 v28, v17
	v_cndmask_b32_e32 v24, v24, v29, vcc
	v_div_scale_f32 v25, s[0:1], v24, v24, 1.0
	v_rcp_f32_e32 v26, v25
	v_mov_b32_e32 v29, v18
	v_mov_b32_e32 v17, v19
	v_pk_add_f32 v[16:17], v[28:29], v[16:17]
	v_fma_f32 v20, -v25, v26, 1.0
	v_fmac_f32_e32 v26, v20, v26
	v_div_scale_f32 v20, vcc, 1.0, v24, 1.0
	v_mul_f32_e32 v21, v20, v26
	v_fma_f32 v22, -v25, v21, v20
	v_fmac_f32_e32 v21, v22, v26
	v_fma_f32 v20, -v25, v21, v20
	v_div_fmas_f32 v20, v20, v26, v21
	v_div_fixup_f32 v24, v20, v24, 1.0
	v_lshlrev_b64 v[26:27], 12, v[142:143]
	v_pk_mul_f32 v[20:21], v[160:161], v[24:25] op_sel_hi:[1,0]
	v_pk_mul_f32 v[22:23], v[158:159], v[24:25] op_sel_hi:[1,0]
	v_lshl_add_u64 v[26:27], s[52:53], 0, v[26:27]
	v_pk_mul_f32 v[22:23], v[14:15], v[22:23]
	v_pk_mul_f32 v[20:21], v[12:13], v[20:21]
	v_lshl_add_u64 v[26:27], v[26:27], 0, v[212:213]
	v_add_f32_e32 v16, v16, v17
	global_store_dwordx4 v[26:27], v[20:23], off nt
	v_fmac_f32_e32 v176, 0x3a800000, v16
	v_mul_f32_e32 v16, 0x4f800000, v176
	v_pk_mul_f32 v[20:21], v[156:157], v[24:25] op_sel_hi:[1,0]
	v_pk_mul_f32 v[22:23], v[44:45], v[24:25] op_sel_hi:[1,0]
	v_pk_mul_f32 v[20:21], v[8:9], v[20:21]
	v_pk_mul_f32 v[22:23], v[10:11], v[22:23]
	v_cmp_gt_f32_e32 vcc, s2, v176
	global_store_dwordx4 v[26:27], v[20:23], off offset:16 nt
	s_nop 1
	v_pk_mul_f32 v[20:21], v[166:167], v[24:25] op_sel_hi:[1,0]
	v_pk_mul_f32 v[22:23], v[154:155], v[24:25] op_sel_hi:[1,0]
	v_cndmask_b32_e32 v25, v176, v16, vcc
	v_sqrt_f32_e32 v28, v25
	v_pk_mul_f32 v[22:23], v[6:7], v[22:23]
	v_pk_mul_f32 v[20:21], v[4:5], v[20:21]
	global_store_dwordx4 v[26:27], v[20:23], off offset:512 nt
	v_pk_mul_f32 v[16:17], v[152:153], v[24:25] op_sel_hi:[1,0]
	v_pk_mul_f32 v[18:19], v[54:55], v[24:25] op_sel_hi:[1,0]
	v_add_u32_e32 v20, -1, v28
	v_fma_f32 v21, -v20, v28, v25
	v_cmp_ge_f32_e64 s[0:1], 0, v21
	v_add_u32_e32 v21, 1, v28
	v_fma_f32 v22, -v21, v28, v25
	v_cndmask_b32_e64 v20, v28, v20, s[0:1]
	v_cmp_lt_f32_e64 s[0:1], 0, v22
	v_pk_mul_f32 v[18:19], v[2:3], v[18:19]
	v_pk_mul_f32 v[16:17], v[0:1], v[16:17]
	v_cndmask_b32_e64 v20, v20, v21, s[0:1]
	v_mul_f32_e32 v21, 0x37800000, v20
	v_cndmask_b32_e32 v20, v20, v21, vcc
	v_cmp_class_f32_e32 vcc, v25, v177
	global_store_dwordx4 v[26:27], v[16:19], off offset:528 nt
	s_nop 0
	v_cndmask_b32_e32 v20, v20, v25, vcc
	v_div_scale_f32 v21, s[0:1], v20, v20, 1.0
	v_rcp_f32_e32 v22, v21
	s_nop 0
	v_fma_f32 v16, -v21, v22, 1.0
	v_fmac_f32_e32 v22, v16, v22
	v_div_scale_f32 v16, vcc, 1.0, v20, 1.0
	v_mul_f32_e32 v17, v16, v22
	v_fma_f32 v18, -v21, v17, v16
	v_fmac_f32_e32 v17, v18, v22
	v_fma_f32 v16, -v21, v17, v16
	v_div_fmas_f32 v16, v16, v22, v17
	v_div_fixup_f32 v16, v16, v20, 1.0
	v_pk_mul_f32 v[18:19], v[150:151], v[16:17] op_sel_hi:[1,0]
	v_pk_mul_f32 v[20:21], v[148:149], v[16:17] op_sel_hi:[1,0]
	v_pk_mul_f32 v[12:13], v[12:13], v[18:19]
	v_lshlrev_b64 v[18:19], 12, v[140:141]
	v_lshl_add_u64 v[18:19], s[52:53], 0, v[18:19]
	v_pk_mul_f32 v[14:15], v[14:15], v[20:21]
	v_lshl_add_u64 v[18:19], v[18:19], 0, v[212:213]
	global_store_dwordx4 v[18:19], v[12:15], off nt
	s_nop 1
	v_pk_mul_f32 v[12:13], v[138:139], v[16:17] op_sel_hi:[1,0]
	v_pk_mul_f32 v[14:15], v[136:137], v[16:17] op_sel_hi:[1,0]
	v_pk_mul_f32 v[8:9], v[8:9], v[12:13]
	v_pk_mul_f32 v[10:11], v[10:11], v[14:15]
	global_store_dwordx4 v[18:19], v[8:11], off offset:16 nt
	s_nop 1
	v_pk_mul_f32 v[8:9], v[132:133], v[16:17] op_sel_hi:[1,0]
	v_pk_mul_f32 v[10:11], v[134:135], v[16:17] op_sel_hi:[1,0]
	v_pk_mul_f32 v[4:5], v[4:5], v[8:9]
	v_pk_mul_f32 v[6:7], v[6:7], v[10:11]
	global_store_dwordx4 v[18:19], v[4:7], off offset:512 nt
	s_nop 1
	v_pk_mul_f32 v[4:5], v[128:129], v[16:17] op_sel_hi:[1,0]
	v_pk_mul_f32 v[6:7], v[130:131], v[16:17] op_sel_hi:[1,0]
	v_pk_mul_f32 v[0:1], v[0:1], v[4:5]
	v_pk_mul_f32 v[2:3], v[2:3], v[6:7]
	global_store_dwordx4 v[18:19], v[0:3], off offset:528 nt
